# v30 plus plain v_pk_add_f32 in the NA and GQA attention job code split into two v_add_f32 (22 sites)
# baseline (speedup 1.0000x reference)
; DI f32x16 mfma32(bf16x8 a, bf16x8 b, f32x16 c) { return __builtin_amdgcn_mfma_f32_32x32x16_bf16(a, b, c, 0, 0, 0); }
; template <int NB>
; DI void softmax_pv(f32x16 (&s)[2], float& mrun, float& lsum, f32x16 (&O)[2], unsigned vaddr) {
;     ...
;   if (NB == 2) {
; #pragma unroll
;     for (int kb = 0; kb < 2; ++kb) {
; #pragma unroll
;       for (int e = 0; e < 16; e += 2) {
;         f32x2 t = {s[kb][e], s[kb][e + 1]};
;         t = t * l2e2 - mb2;
;         f32x2 pv;
;         pv[0] = __builtin_amdgcn_exp2f(t[0]);
;         pv[1] = __builtin_amdgcn_exp2f(t[1]);
;         s[kb][e] = pv[0];
;         s[kb][e + 1] = pv[1];
;         ps2 += pv;
;       }
;       u32x4 pp[2];
; #pragma unroll
;       for (int st = 0; st < 2; ++st)
; #pragma unroll
;         for (int j = 0; j < 4; ++j) pp[st][j] = pk_bf16(s[kb][8 * st + 2 * j], s[kb][8 * st + 2 * j + 1]);
;       __builtin_amdgcn_sched_barrier(0);
;       __builtin_amdgcn_s_setprio(1);
; #pragma unroll
;       for (int st = 0; st < 2; ++st) {
;         const bf16x8 pf = as_bf16x8(pp[st]);
; #pragma unroll
;         for (int db = 0; db < 2; ++db) {
;           const int ix = ((kb * 2 + st) * 2 + db) * 2;
;           u32x4 av;
;           av[0] = vf[ix][0]; av[1] = vf[ix][1]; av[2] = vf[ix + 1][0]; av[3] = vf[ix + 1][1];
;           O[db] = mfma32(as_bf16x8(av), pf, O[db]);
;         }
;       }
;       __builtin_amdgcn_s_setprio(0);
;       __builtin_amdgcn_sched_barrier(0);
;     }
;     ...
;   lsum = lsum * alpha + (ps2[0] + ps2[1]);
.LBB0_474:
	v_mul_f32_e32 v226, 0x3fb8aa3b, v224
	v_fma_f32 v112, v112, s28, -v226
	v_fma_f32 v113, v113, s28, -v226
	s_nop 0
	v_exp_f32_e32 v228, v112
	v_exp_f32_e32 v229, v113
	v_fma_f32 v112, v114, s28, -v226
	v_fma_f32 v113, v115, s28, -v226
	s_nop 0
	v_exp_f32_e32 v230, v112
	v_exp_f32_e32 v231, v113
	v_fma_f32 v112, v116, s28, -v226
	v_fma_f32 v113, v117, s28, -v226
	s_nop 0
	v_exp_f32_e32 v232, v112
	v_exp_f32_e32 v233, v113
	v_fma_f32 v112, v118, s28, -v226
	v_fma_f32 v113, v119, s28, -v226
	v_cvt_pk_bf16_f32 v114, v232, v233
	v_exp_f32_e32 v238, v112
	v_exp_f32_e32 v239, v113
	v_fma_f32 v112, v120, s28, -v226
	v_fma_f32 v113, v121, s28, -v226
	v_cvt_pk_bf16_f32 v115, v238, v239
	v_exp_f32_e32 v120, v112
	v_exp_f32_e32 v121, v113
	v_fma_f32 v112, v122, s28, -v226
	v_fma_f32 v113, v123, s28, -v226
	v_cvt_pk_bf16_f32 v116, v120, v121
	v_exp_f32_e32 v122, v112
	v_exp_f32_e32 v123, v113
	v_fma_f32 v112, v124, s28, -v226
	v_fma_f32 v113, v125, s28, -v226
	v_cvt_pk_bf16_f32 v117, v122, v123
	v_exp_f32_e32 v124, v112
	v_exp_f32_e32 v125, v113
	v_fma_f32 v112, v126, s28, -v226
	v_fma_f32 v113, v127, s28, -v226
	v_cvt_pk_bf16_f32 v118, v124, v125
	v_exp_f32_e32 v126, v112
	v_exp_f32_e32 v127, v113
	v_cvt_pk_bf16_f32 v112, v228, v229
	v_cvt_pk_bf16_f32 v113, v230, v231
	v_cvt_pk_bf16_f32 v119, v126, v127
	s_nop 0
	v_mfma_f32_32x32x16_bf16 v[64:79], v[168:171], v[112:115], v[64:79]
	v_mfma_f32_32x32x16_bf16 v[80:95], v[164:167], v[112:115], v[80:95]
	v_add_f32_e64 v112, v228, 0
	v_add_f32_e64 v113, v229, 0
	v_add_f32_e64 v112, v230, v112
	v_add_f32_e64 v113, v231, v113
	v_add_f32_e64 v112, v232, v112
	v_add_f32_e64 v113, v233, v113
	v_add_f32_e32 v112, v238, v112
	v_add_f32_e32 v113, v239, v113
	v_mfma_f32_32x32x16_bf16 v[64:79], v[160:163], v[116:119], v[64:79]
	v_add_f32_e64 v112, v120, v112
	v_add_f32_e64 v113, v121, v113
	v_add_f32_e64 v112, v122, v112
	v_add_f32_e64 v113, v123, v113
	v_add_f32_e64 v112, v124, v112
	v_add_f32_e64 v113, v125, v113
	v_add_f32_e32 v112, v126, v112
	v_add_f32_e32 v113, v127, v113
	v_mfma_f32_32x32x16_bf16 v[80:95], v[156:159], v[116:119], v[80:95]
	s_nop 0
	v_fma_f32 v96, v96, s28, -v226
	v_fma_f32 v97, v97, s28, -v226
	v_exp_f32_e32 v114, v96
	v_exp_f32_e32 v115, v97
	v_fma_f32 v96, v98, s28, -v226
	v_fma_f32 v97, v99, s28, -v226
	s_nop 0
	v_exp_f32_e32 v116, v96
	v_exp_f32_e32 v117, v97
	v_fma_f32 v96, v100, s28, -v226
	v_fma_f32 v97, v101, s28, -v226
	s_nop 0
	v_exp_f32_e32 v118, v96
	v_exp_f32_e32 v119, v97
	v_fma_f32 v96, v102, s28, -v226
	v_fma_f32 v97, v103, s28, -v226
	v_cvt_pk_bf16_f32 v98, v118, v119
	v_exp_f32_e32 v120, v96
	v_exp_f32_e32 v121, v97
	v_fma_f32 v96, v104, s28, -v226
	v_fma_f32 v97, v105, s28, -v226
	v_cvt_pk_bf16_f32 v99, v120, v121
	v_exp_f32_e32 v104, v96
	v_exp_f32_e32 v105, v97
	v_fma_f32 v96, v106, s28, -v226
	v_fma_f32 v97, v107, s28, -v226
	v_cvt_pk_bf16_f32 v100, v104, v105
	v_exp_f32_e32 v106, v96
	v_exp_f32_e32 v107, v97
	v_fma_f32 v96, v108, s28, -v226
	v_fma_f32 v97, v109, s28, -v226
	v_cvt_pk_bf16_f32 v101, v106, v107
	v_exp_f32_e32 v108, v96
	v_exp_f32_e32 v109, v97
	v_fma_f32 v96, v110, s28, -v226
	v_fma_f32 v97, v111, s28, -v226
	v_cvt_pk_bf16_f32 v102, v108, v109
	v_exp_f32_e32 v110, v96
	v_exp_f32_e32 v111, v97
	v_cvt_pk_bf16_f32 v96, v114, v115
	v_cvt_pk_bf16_f32 v97, v116, v117
	v_cvt_pk_bf16_f32 v103, v110, v111
	s_nop 0
	v_mfma_f32_32x32x16_bf16 v[64:79], v[152:155], v[96:99], v[64:79]
	v_mfma_f32_32x32x16_bf16 v[80:95], v[10:13], v[96:99], v[80:95]
	v_mfma_f32_32x32x16_bf16 v[64:79], v[6:9], v[100:103], v[64:79]
	v_add_f32_e64 v6, v114, v112
	v_add_f32_e64 v7, v115, v113
	v_add_f32_e64 v6, v116, v6
	v_add_f32_e64 v7, v117, v7
	v_add_f32_e64 v6, v118, v6
	v_add_f32_e64 v7, v119, v7
	v_add_f32_e32 v6, v120, v6
	v_add_f32_e32 v7, v121, v7
	v_mfma_f32_32x32x16_bf16 v[80:95], v[2:5], v[100:103], v[80:95]
	v_add_f32_e64 v6, v104, v6
	v_add_f32_e64 v7, v105, v7
	v_add_f32_e64 v6, v106, v6
	v_add_f32_e64 v7, v107, v7
	v_add_f32_e64 v6, v108, v6
	v_add_f32_e64 v7, v109, v7
	v_add_f32_e32 v6, v110, v6
	v_add_f32_e32 v7, v111, v7
	s_nop 0
	v_add_f32_e32 v2, v6, v7
	v_mov_b64_e32 v[126:127], v[78:79]
	s_nop 1
	v_mov_b64_e32 v[110:111], v[94:95]
	v_fmac_f32_e32 v2, v192, v0
	v_mov_b64_e32 v[124:125], v[76:77]
	v_mov_b64_e32 v[122:123], v[74:75]
	v_mov_b64_e32 v[120:121], v[72:73]
	v_mov_b64_e32 v[118:119], v[70:71]
	v_mov_b64_e32 v[116:117], v[68:69]
	v_mov_b64_e32 v[114:115], v[66:67]
	v_mov_b64_e32 v[112:113], v[64:65]
	v_mov_b64_e32 v[108:109], v[92:93]
	v_mov_b64_e32 v[106:107], v[90:91]
	v_mov_b64_e32 v[104:105], v[88:89]
	v_mov_b64_e32 v[102:103], v[86:87]
	v_mov_b64_e32 v[100:101], v[84:85]
	v_mov_b64_e32 v[98:99], v[82:83]
	v_mov_b64_e32 v[96:97], v[80:81]
	s_branch .LBB0_513
; DI f32x16 mfma32(bf16x8 a, bf16x8 b, f32x16 c) { return __builtin_amdgcn_mfma_f32_32x32x16_bf16(a, b, c, 0, 0, 0); }
; DI float xmax32(float x) { auto r = __builtin_amdgcn_permlane32_swap(__float_as_uint(x), __float_as_uint(x), false, false); return fmaxf(__uint_as_float(r[0]), __uint_as_float(r[1])); }
; template <int NB>
; DI void softmax_pv(f32x16 (&s)[2], float& mrun, float& lsum, f32x16 (&O)[2], unsigned vaddr) {
;   u32x2 vf[16];
;   u32x2 vf8[8];
;   if (NB == 2) tr_read_vtile(vf, vaddr);
;   else tr_read_vtile8(vf8, vaddr);
;   float mx = -1e30f;
; #pragma unroll
;   for (int kb = 0; kb < NB; ++kb)
; #pragma unroll
;     for (int e = 0; e < 16; ++e) mx = fmaxf(mx, s[kb][e]);
;   mx = xmax32(mx);
;   constexpr float THR = 8.f;
;   float alpha = 1.f;
;   if (__builtin_amdgcn_ballot_w64(mx - mrun > THR) != 0ull) {
;     const float mnew = fmaxf(mrun, mx);
;     alpha = __builtin_amdgcn_exp2f((mrun - mnew) * L2E);
;     mrun = mnew;
; #pragma unroll
;     for (int e = 0; e < 16; ++e) { O[0][e] *= alpha; O[1][e] *= alpha; }
; template <int kind>
; __device__ void attn_job(const Params& p, int layer, int idx, char* smem) {
;     ...
;     if (kind == 1 && i >= 4) {
;       const int kr = R0 + i - 4;
;       if (kr >= r0A && kr < r0A + 9) {
;         f32x16 s[2];
; #pragma unroll
;         for (int st = 0; st < 4; ++st) s[0] = mfma32(ld_frag16(Kb + (k0 + tq) * KS_STRIDE + 16 * st + 8 * hh), qf[st], st == 0 ? zero16 : s[0]);
;         const bool rowvalid = (kr >= r0l) && (kr < r0l + 8);
;         const unsigned m = rowvalid ? colmask : 0u;
;         const float* brow = rpbs + (kr - qrow_l + 7) * 32 + dcbase;
; #pragma unroll
;         for (int e = 0; e < 16; ++e) {
;           const float bias = brow[(e & 3) + 8 * (e >> 2)];
;           s[0][e] = ((m >> e) & 1u) ? s[0][e] + bias : -1e30f;
;         }
;         softmax_pv<1>(s, mrun, lsum, O, (unsigned)(size_t)Vb + vlane_off + (unsigned)(k0 * KS_STRIDE * 2));
.LBB0_475:
	s_add_i32 s0, s11, s13
	s_cmp_ge_i32 s0, s6
	s_cselect_b64 s[16:17], -1, 0
	s_cmp_lt_i32 s0, s10
	s_cselect_b64 s[20:21], -1, 0
	s_and_b64 s[16:17], s[16:17], s[20:21]
	s_andn2_b64 vcc, exec, s[16:17]
	s_cbranch_vccnz .LBB0_512
	v_add3_u32 v0, s14, v185, v180
	ds_read_b128 v[2:5], v0
	ds_read_b128 v[6:9], v0 offset:32
	ds_read_b128 v[10:13], v0 offset:64
	ds_read_b128 v[80:83], v0 offset:96
	v_cmp_ge_i32_e32 vcc, s0, v184
	v_cmp_lt_i32_e64 s[0:1], s0, v186
	s_and_b64 vcc, vcc, s[0:1]
	v_mov_b32_e32 v15, 0xf149f2ca
	v_mov_b32_e32 v14, 0xf149f2ca
	v_cndmask_b32_e32 v0, 0, v179, vcc
	s_waitcnt lgkmcnt(3)
	v_mfma_f32_32x32x16_bf16 v[64:79], v[2:5], v[136:139], v[16:31]
	s_waitcnt lgkmcnt(2)
	v_mfma_f32_32x32x16_bf16 v[64:79], v[6:9], v[128:131], v[64:79]
	s_waitcnt lgkmcnt(1)
	v_mfma_f32_32x32x16_bf16 v[64:79], v[10:13], v[132:135], v[64:79]
	s_waitcnt lgkmcnt(0)
	v_mfma_f32_32x32x16_bf16 v[64:79], v[80:83], v[140:143], v[64:79]
	ds_read2_b32 v[80:81], v189 offset0:2 offset1:3
	ds_read2_b32 v[82:83], v189 offset0:8 offset1:9
	ds_read2_b32 v[6:7], v189 offset0:16 offset1:17
	ds_read2_b32 v[8:9], v189 offset0:18 offset1:19
	ds_read2_b32 v[10:11], v189 offset0:24 offset1:25
	ds_read2_b32 v[12:13], v189 offset0:26 offset1:27
	ds_read2_b32 v[2:3], v189 offset1:1
	ds_read2_b32 v[4:5], v189 offset0:10 offset1:11
	s_waitcnt lgkmcnt(0)
	s_nop 2
	v_add_f32_e32 v2, v64, v2
	v_add_f32_e32 v3, v65, v3
	v_add_f32_e32 v80, v66, v80
	v_add_f32_e32 v81, v67, v81
	v_add_f32_e32 v82, v68, v82
	v_add_f32_e32 v83, v69, v83
	v_add_f32_e32 v4, v70, v4
	v_add_f32_e32 v5, v71, v5
	v_add_f32_e32 v6, v72, v6
	v_add_f32_e32 v7, v73, v7
	v_add_f32_e32 v8, v74, v8
	v_add_f32_e32 v9, v75, v9
	v_add_f32_e32 v10, v76, v10
	v_add_f32_e32 v11, v77, v11
	v_add_f32_e32 v12, v78, v12
	v_add_f32_e32 v13, v79, v13
	v_bfe_i32 v64, v0, 0, 1
	v_bfe_i32 v65, v0, 1, 1
	v_bfe_i32 v66, v0, 2, 1
	v_bfe_i32 v67, v0, 3, 1
	v_bfi_b32 v14, v64, v2, s24
	v_bfi_b32 v15, v65, v3, s24
	v_bfi_b32 v80, v66, v80, s24
	v_bfi_b32 v81, v67, v81, s24
	v_bfe_i32 v64, v0, 4, 1
	v_bfe_i32 v65, v0, 5, 1
	v_bfe_i32 v66, v0, 6, 1
	v_bfe_i32 v67, v0, 7, 1
	v_bfi_b32 v82, v64, v82, s24
	v_bfi_b32 v83, v65, v83, s24
	v_bfi_b32 v68, v66, v4, s24
	v_bfi_b32 v69, v67, v5, s24
	v_bfe_i32 v64, v0, 8, 1
	v_bfe_i32 v65, v0, 9, 1
	v_bfe_i32 v66, v0, 10, 1
	v_bfe_i32 v67, v0, 11, 1
	v_bfi_b32 v70, v64, v6, s24
	v_bfi_b32 v71, v65, v7, s24
	v_bfi_b32 v72, v66, v8, s24
	v_bfi_b32 v73, v67, v9, s24
	v_bfe_i32 v64, v0, 12, 1
	v_bfe_i32 v65, v0, 13, 1
	v_bfe_i32 v66, v0, 14, 1
	v_bfe_i32 v67, v0, 15, 1
	v_bfi_b32 v74, v64, v10, s24
	v_bfi_b32 v75, v65, v11, s24
	v_bfi_b32 v76, v66, v12, s24
	v_bfi_b32 v77, v67, v13, s24
	v_add_u32_e32 v0, s3, v187
	ds_read_b64_tr_b16 v[64:65], v0 offset:0
	ds_read_b64_tr_b16 v[66:67], v0 offset:1152
	ds_read_b64_tr_b16 v[10:11], v0 offset:64
	ds_read_b64_tr_b16 v[12:13], v0 offset:1216
	ds_read_b64_tr_b16 v[6:7], v0 offset:2304
	ds_read_b64_tr_b16 v[8:9], v0 offset:3456
	ds_read_b64_tr_b16 v[2:3], v0 offset:2368
	ds_read_b64_tr_b16 v[4:5], v0 offset:3520
	s_waitcnt lgkmcnt(0)
	v_max3_f32 v0, v14, s24, v15
	v_max3_f32 v0, v0, v80, v81
	v_max3_f32 v0, v0, v82, v83
	v_max3_f32 v0, v0, v68, v69
	v_max3_f32 v0, v0, v70, v71
	v_max3_f32 v0, v0, v72, v73
	v_max3_f32 v0, v0, v74, v75
	v_max3_f32 v0, v0, v76, v77
	v_mov_b32_e32 v78, v0
	s_nop 1
	v_permlane32_swap_b32_e32 v0, v78
	v_max_f32_e32 v78, v78, v78
	v_max_f32_e32 v0, v0, v0
	v_max_f32_e32 v0, v0, v78
	v_sub_f32_e32 v78, v0, v193
	v_cmp_lt_f32_e32 vcc, s25, v78
	s_cbranch_vccz .LBB0_510
	v_max_f32_e32 v0, v0, v0
	v_max_f32_e32 v78, v193, v193
	v_max_f32_e32 v78, v78, v0
	v_sub_f32_e32 v0, v193, v78
	v_mul_f32_e32 v0, 0x3fb8aa3b, v0
	v_exp_f32_e32 v0, v0
	v_mov_b32_e32 v193, v78
	v_pk_mul_f32 v[46:47], v[46:47], v[0:1] op_sel_hi:[1,0]
	v_pk_mul_f32 v[44:45], v[44:45], v[0:1] op_sel_hi:[1,0]
	v_pk_mul_f32 v[42:43], v[42:43], v[0:1] op_sel_hi:[1,0]
	v_pk_mul_f32 v[40:41], v[40:41], v[0:1] op_sel_hi:[1,0]
	v_pk_mul_f32 v[38:39], v[38:39], v[0:1] op_sel_hi:[1,0]
	v_pk_mul_f32 v[36:37], v[36:37], v[0:1] op_sel_hi:[1,0]
	v_pk_mul_f32 v[34:35], v[34:35], v[0:1] op_sel_hi:[1,0]
	v_pk_mul_f32 v[32:33], v[32:33], v[0:1] op_sel_hi:[1,0]
	v_pk_mul_f32 v[62:63], v[62:63], v[0:1] op_sel_hi:[1,0]
	v_pk_mul_f32 v[60:61], v[60:61], v[0:1] op_sel_hi:[1,0]
	v_pk_mul_f32 v[58:59], v[58:59], v[0:1] op_sel_hi:[1,0]
	v_pk_mul_f32 v[56:57], v[56:57], v[0:1] op_sel_hi:[1,0]
	v_pk_mul_f32 v[54:55], v[54:55], v[0:1] op_sel_hi:[1,0]
	v_pk_mul_f32 v[52:53], v[52:53], v[0:1] op_sel_hi:[1,0]
	v_pk_mul_f32 v[50:51], v[50:51], v[0:1] op_sel_hi:[1,0]
	v_pk_mul_f32 v[48:49], v[48:49], v[0:1] op_sel_hi:[1,0]
	s_branch .LBB0_511

; DI f32x16 mfma32(bf16x8 a, bf16x8 b, f32x16 c) { return __builtin_amdgcn_mfma_f32_32x32x16_bf16(a, b, c, 0, 0, 0); }
; template <int NB>
; DI void softmax_pv(f32x16 (&s)[2], float& mrun, float& lsum, f32x16 (&O)[2], unsigned vaddr) {
;     ...
; #pragma unroll
;     for (int e = 0; e < 16; e += 2) {
;       f32x2 t = {s[0][e], s[0][e + 1]};
;       t = t * l2e2 - mb2;
;       f32x2 pv;
;       pv[0] = __builtin_amdgcn_exp2f(t[0]);
;       pv[1] = __builtin_amdgcn_exp2f(t[1]);
;       s[0][e] = pv[0];
;       s[0][e + 1] = pv[1];
;       ps2 += pv;
;     }
;     __builtin_amdgcn_s_setprio(1);
; #pragma unroll
;     for (int st = 0; st < 2; ++st) {
;       u32x4 pp;
; #pragma unroll
;       for (int j = 0; j < 4; ++j) pp[j] = pk_bf16(s[0][8 * st + 2 * j], s[0][8 * st + 2 * j + 1]);
;       const bf16x8 pf = as_bf16x8(pp);
; #pragma unroll
;       for (int db = 0; db < 2; ++db) {
;         const int ix = (st * 2 + db) * 2;
;         u32x4 av;
;         av[0] = vf8[ix][0]; av[1] = vf8[ix][1]; av[2] = vf8[ix + 1][0]; av[3] = vf8[ix + 1][1];
;         O[db] = mfma32(as_bf16x8(av), pf, O[db]);
;       }
;     }
;     __builtin_amdgcn_s_setprio(0);
;   }
;   lsum = lsum * alpha + (ps2[0] + ps2[1]);
.LBB0_511:
	v_mul_f32_e32 v78, 0x3fb8aa3b, v193
	v_fma_f32 v14, v14, s28, -v78
	v_fma_f32 v15, v15, s28, -v78
	v_fma_f32 v68, v68, s28, -v78
	v_fma_f32 v69, v69, s28, -v78
	v_exp_f32_e32 v14, v14
	v_exp_f32_e32 v15, v15
	v_exp_f32_e32 v84, v68
	v_exp_f32_e32 v85, v69
	v_fma_f32 v68, v70, s28, -v78
	v_fma_f32 v69, v71, s28, -v78
	v_fma_f32 v80, v80, s28, -v78
	v_fma_f32 v81, v81, s28, -v78
	v_exp_f32_e32 v86, v68
	v_exp_f32_e32 v87, v69
	v_fma_f32 v68, v72, s28, -v78
	v_fma_f32 v69, v73, s28, -v78
	v_fma_f32 v82, v82, s28, -v78
	v_fma_f32 v83, v83, s28, -v78
	v_exp_f32_e32 v72, v68
	v_exp_f32_e32 v73, v69
	v_fma_f32 v68, v74, s28, -v78
	v_fma_f32 v69, v75, s28, -v78
	v_exp_f32_e32 v80, v80
	v_exp_f32_e32 v74, v68
	v_exp_f32_e32 v75, v69
	v_fma_f32 v68, v76, s28, -v78
	v_fma_f32 v69, v77, s28, -v78
	v_exp_f32_e32 v81, v81
	v_exp_f32_e32 v82, v82
	v_exp_f32_e32 v83, v83
	v_exp_f32_e32 v76, v68
	v_exp_f32_e32 v77, v69
	s_nop 0
	v_cvt_pk_bf16_f32 v68, v14, v15
	v_cvt_pk_bf16_f32 v69, v80, v81
	v_cvt_pk_bf16_f32 v70, v82, v83
	v_cvt_pk_bf16_f32 v71, v84, v85
	s_nop 1
	v_mfma_f32_32x32x16_bf16 v[32:47], v[64:67], v[68:71], v[32:47]
	v_mfma_f32_32x32x16_bf16 v[48:63], v[10:13], v[68:71], v[48:63]
	v_cvt_pk_bf16_f32 v10, v86, v87
	v_cvt_pk_bf16_f32 v11, v72, v73
	v_cvt_pk_bf16_f32 v12, v74, v75
	v_cvt_pk_bf16_f32 v13, v76, v77
	s_nop 1
	v_mfma_f32_32x32x16_bf16 v[32:47], v[6:9], v[10:13], v[32:47]
	v_add_f32_e64 v6, v14, 0
	v_add_f32_e64 v7, v15, 0
	v_add_f32_e64 v6, v80, v6
	v_add_f32_e64 v7, v81, v7
	v_add_f32_e64 v6, v82, v6
	v_add_f32_e64 v7, v83, v7
	v_add_f32_e32 v6, v84, v6
	v_add_f32_e32 v7, v85, v7
	v_mfma_f32_32x32x16_bf16 v[48:63], v[2:5], v[10:13], v[48:63]
	v_add_f32_e64 v6, v86, v6
	v_add_f32_e64 v7, v87, v7
	v_add_f32_e64 v6, v72, v6
	v_add_f32_e64 v7, v73, v7
	v_add_f32_e64 v6, v74, v6
	v_add_f32_e64 v7, v75, v7
	v_add_f32_e32 v6, v76, v6
	v_add_f32_e32 v7, v77, v7
	s_nop 0
	v_add_f32_e32 v2, v6, v7
	v_fmac_f32_e32 v2, v192, v0
	v_mov_b32_e32 v223, v47
	v_mov_b32_e32 v222, v46
	v_mov_b32_e32 v221, v45
	v_mov_b32_e32 v220, v44
	v_mov_b32_e32 v219, v43
	v_mov_b32_e32 v218, v42
	v_mov_b32_e32 v217, v41
	v_mov_b32_e32 v216, v40
	v_mov_b32_e32 v215, v39
	v_mov_b32_e32 v214, v38
	v_mov_b32_e32 v213, v37
	v_mov_b32_e32 v212, v36
	v_mov_b32_e32 v211, v35
	v_mov_b32_e32 v210, v34
	v_mov_b32_e32 v209, v33
	v_mov_b32_e32 v208, v32
	v_mov_b32_e32 v207, v63
	v_mov_b32_e32 v206, v62
	v_mov_b32_e32 v205, v61
	v_mov_b32_e32 v204, v60
	v_mov_b32_e32 v203, v59
	v_mov_b32_e32 v202, v58
	v_mov_b32_e32 v201, v57
	v_mov_b32_e32 v200, v56
	v_mov_b32_e32 v199, v55
	v_mov_b32_e32 v198, v54
	v_mov_b32_e32 v197, v53
	v_mov_b32_e32 v196, v52
	v_mov_b32_e32 v195, v51
	v_mov_b32_e32 v194, v50
	v_mov_b32_e32 v15, v49
	v_mov_b32_e32 v14, v48
	v_mov_b32_e32 v192, v2

; DI f32x16 mfma32(bf16x8 a, bf16x8 b, f32x16 c) { return __builtin_amdgcn_mfma_f32_32x32x16_bf16(a, b, c, 0, 0, 0); }
; template <int NB>
; DI void softmax_pv(f32x16 (&s)[2], float& mrun, float& lsum, f32x16 (&O)[2], unsigned vaddr) {
;     ...
;   if (NB == 2) {
; #pragma unroll
;     for (int kb = 0; kb < 2; ++kb) {
; #pragma unroll
;       for (int e = 0; e < 16; e += 2) {
;         f32x2 t = {s[kb][e], s[kb][e + 1]};
;         t = t * l2e2 - mb2;
;         f32x2 pv;
;         pv[0] = __builtin_amdgcn_exp2f(t[0]);
;         pv[1] = __builtin_amdgcn_exp2f(t[1]);
;         s[kb][e] = pv[0];
;         s[kb][e + 1] = pv[1];
;         ps2 += pv;
;       }
;       u32x4 pp[2];
; #pragma unroll
;       for (int st = 0; st < 2; ++st)
; #pragma unroll
;         for (int j = 0; j < 4; ++j) pp[st][j] = pk_bf16(s[kb][8 * st + 2 * j], s[kb][8 * st + 2 * j + 1]);
;       __builtin_amdgcn_sched_barrier(0);
;       __builtin_amdgcn_s_setprio(1);
; #pragma unroll
;       for (int st = 0; st < 2; ++st) {
;         const bf16x8 pf = as_bf16x8(pp[st]);
; #pragma unroll
;         for (int db = 0; db < 2; ++db) {
;           const int ix = ((kb * 2 + st) * 2 + db) * 2;
;           u32x4 av;
;           av[0] = vf[ix][0]; av[1] = vf[ix][1]; av[2] = vf[ix + 1][0]; av[3] = vf[ix + 1][1];
;           O[db] = mfma32(as_bf16x8(av), pf, O[db]);
;         }
;       }
;       __builtin_amdgcn_s_setprio(0);
;       __builtin_amdgcn_sched_barrier(0);
;     }
;     ...
;   lsum = lsum * alpha + (ps2[0] + ps2[1]);
; template <int kind>
; __device__ void attn_job(const Params& p, int layer, int idx, char* smem) {
;     ...
;   for (int i = 0; i < ntiles; ++i) {
.LBB0_523:
	v_mul_f32_e32 v144, 0x3fb8aa3b, v145
	v_fma_f32 v66, v66, s28, -v144
	v_fma_f32 v67, v67, s28, -v144
	s_add_i32 s7, s7, 1
	v_exp_f32_e32 v150, v66
	v_exp_f32_e32 v151, v67
	v_fma_f32 v66, v68, s28, -v144
	v_fma_f32 v67, v69, s28, -v144
	s_nop 0
	v_exp_f32_e32 v152, v66
	v_exp_f32_e32 v153, v67
	v_fma_f32 v66, v70, s28, -v144
	v_fma_f32 v67, v71, s28, -v144
	s_nop 0
	v_exp_f32_e32 v154, v66
	v_exp_f32_e32 v155, v67
	v_fma_f32 v66, v72, s28, -v144
	v_fma_f32 v67, v73, s28, -v144
	v_cvt_pk_bf16_f32 v68, v154, v155
	v_exp_f32_e32 v156, v66
	v_exp_f32_e32 v157, v67
	v_fma_f32 v66, v74, s28, -v144
	v_fma_f32 v67, v75, s28, -v144
	v_cvt_pk_bf16_f32 v69, v156, v157
	v_exp_f32_e32 v74, v66
	v_exp_f32_e32 v75, v67
	v_fma_f32 v66, v76, s28, -v144
	v_fma_f32 v67, v77, s28, -v144
	v_cvt_pk_bf16_f32 v70, v74, v75
	v_exp_f32_e32 v76, v66
	v_exp_f32_e32 v77, v67
	v_fma_f32 v66, v78, s28, -v144
	v_fma_f32 v67, v79, s28, -v144
	v_cvt_pk_bf16_f32 v71, v76, v77
	v_exp_f32_e32 v78, v66
	v_exp_f32_e32 v79, v67
	v_fma_f32 v66, v80, s28, -v144
	v_fma_f32 v67, v81, s28, -v144
	v_cvt_pk_bf16_f32 v72, v78, v79
	v_exp_f32_e32 v80, v66
	v_exp_f32_e32 v81, v67
	v_cvt_pk_bf16_f32 v66, v150, v151
	v_cvt_pk_bf16_f32 v67, v152, v153
	v_cvt_pk_bf16_f32 v73, v80, v81
	s_waitcnt lgkmcnt(0)
	s_nop 0
	v_mfma_f32_32x32x16_bf16 v[18:33], v[134:137], v[66:69], v[18:33]
	v_mfma_f32_32x32x16_bf16 v[2:17], v[130:133], v[66:69], v[2:17]
	v_add_f32_e64 v66, v150, 0
	v_add_f32_e64 v67, v151, 0
	v_add_f32_e64 v66, v152, v66
	v_add_f32_e64 v67, v153, v67
	v_add_f32_e64 v66, v154, v66
	v_add_f32_e64 v67, v155, v67
	v_add_f32_e32 v66, v156, v66
	v_add_f32_e32 v67, v157, v67
	v_mfma_f32_32x32x16_bf16 v[18:33], v[126:129], v[70:73], v[18:33]
	v_add_f32_e64 v66, v74, v66
	v_add_f32_e64 v67, v75, v67
	v_add_f32_e64 v66, v76, v66
	v_add_f32_e64 v67, v77, v67
	v_add_f32_e64 v66, v78, v66
	v_add_f32_e64 v67, v79, v67
	v_add_f32_e32 v66, v80, v66
	v_add_f32_e32 v67, v81, v67
	v_mfma_f32_32x32x16_bf16 v[2:17], v[122:125], v[70:73], v[2:17]
	s_nop 0
	v_fma_f32 v50, v50, s28, -v144
	v_fma_f32 v51, v51, s28, -v144
	v_exp_f32_e32 v68, v50
	v_exp_f32_e32 v69, v51
	v_fma_f32 v50, v52, s28, -v144
	v_fma_f32 v51, v53, s28, -v144
	s_nop 0
	v_exp_f32_e32 v70, v50
	v_exp_f32_e32 v71, v51
	v_fma_f32 v50, v54, s28, -v144
	v_fma_f32 v51, v55, s28, -v144
	s_nop 0
	v_exp_f32_e32 v72, v50
	v_exp_f32_e32 v73, v51
	v_fma_f32 v50, v56, s28, -v144
	v_fma_f32 v51, v57, s28, -v144
	v_cvt_pk_bf16_f32 v52, v72, v73
	v_exp_f32_e32 v74, v50
	v_exp_f32_e32 v75, v51
	v_fma_f32 v50, v58, s28, -v144
	v_fma_f32 v51, v59, s28, -v144
	v_cvt_pk_bf16_f32 v53, v74, v75
	v_exp_f32_e32 v58, v50
	v_exp_f32_e32 v59, v51
	v_fma_f32 v50, v60, s28, -v144
	v_fma_f32 v51, v61, s28, -v144
	v_cvt_pk_bf16_f32 v54, v58, v59
	v_exp_f32_e32 v60, v50
	v_exp_f32_e32 v61, v51
	v_fma_f32 v50, v62, s28, -v144
	v_fma_f32 v51, v63, s28, -v144
	v_cvt_pk_bf16_f32 v55, v60, v61
	v_exp_f32_e32 v62, v50
	v_exp_f32_e32 v63, v51
	v_fma_f32 v50, v64, s28, -v144
	v_fma_f32 v51, v65, s28, -v144
	v_cvt_pk_bf16_f32 v56, v62, v63
	v_exp_f32_e32 v64, v50
	v_exp_f32_e32 v65, v51
	v_cvt_pk_bf16_f32 v50, v68, v69
	v_cvt_pk_bf16_f32 v51, v70, v71
	v_cvt_pk_bf16_f32 v57, v64, v65
	s_nop 0
	v_mfma_f32_32x32x16_bf16 v[18:33], v[118:121], v[50:53], v[18:33]
	v_mfma_f32_32x32x16_bf16 v[2:17], v[114:117], v[50:53], v[2:17]
	v_add_f32_e64 v50, v68, v66
	v_add_f32_e64 v51, v69, v67
	v_add_f32_e64 v50, v70, v50
	v_add_f32_e64 v51, v71, v51
	v_add_f32_e64 v50, v72, v50
	v_add_f32_e64 v51, v73, v51
	v_add_f32_e32 v50, v74, v50
	v_add_f32_e32 v51, v75, v51
	v_mfma_f32_32x32x16_bf16 v[18:33], v[110:113], v[54:57], v[18:33]
	v_add_f32_e64 v50, v58, v50
	v_add_f32_e64 v51, v59, v51
	v_add_f32_e64 v50, v60, v50
	v_add_f32_e64 v51, v61, v51
	v_add_f32_e64 v50, v62, v50
	v_add_f32_e64 v51, v63, v51
	v_add_f32_e32 v50, v64, v50
	v_add_f32_e32 v51, v65, v51
	v_mfma_f32_32x32x16_bf16 v[2:17], v[106:109], v[54:57], v[2:17]
	s_nop 0
	v_add_f32_e32 v106, v50, v51
	s_add_i32 s6, s6, 64
	s_cmp_eq_u32 s7, 35
	v_fmac_f32_e32 v106, v149, v146
	s_cbranch_scc1 .LBB0_525
	v_mov_b32_e32 v149, v106
	s_branch .LBB0_520

; DI f32x16 mfma32(bf16x8 a, bf16x8 b, f32x16 c) { return __builtin_amdgcn_mfma_f32_32x32x16_bf16(a, b, c, 0, 0, 0); }
; template <int NB>
; DI void softmax_pv(f32x16 (&s)[2], float& mrun, float& lsum, f32x16 (&O)[2], unsigned vaddr) {
;     ...
;   if (NB == 2) {
; #pragma unroll
;     for (int kb = 0; kb < 2; ++kb) {
; #pragma unroll
;       for (int e = 0; e < 16; e += 2) {
;         f32x2 t = {s[kb][e], s[kb][e + 1]};
;         t = t * l2e2 - mb2;
;         f32x2 pv;
;         pv[0] = __builtin_amdgcn_exp2f(t[0]);
;         pv[1] = __builtin_amdgcn_exp2f(t[1]);
;         s[kb][e] = pv[0];
;         s[kb][e + 1] = pv[1];
;         ps2 += pv;
;       }
;       u32x4 pp[2];
; #pragma unroll
;       for (int st = 0; st < 2; ++st)
; #pragma unroll
;         for (int j = 0; j < 4; ++j) pp[st][j] = pk_bf16(s[kb][8 * st + 2 * j], s[kb][8 * st + 2 * j + 1]);
;       __builtin_amdgcn_sched_barrier(0);
;       __builtin_amdgcn_s_setprio(1);
; #pragma unroll
;       for (int st = 0; st < 2; ++st) {
;         const bf16x8 pf = as_bf16x8(pp[st]);
; #pragma unroll
;         for (int db = 0; db < 2; ++db) {
;           const int ix = ((kb * 2 + st) * 2 + db) * 2;
;           u32x4 av;
;           av[0] = vf[ix][0]; av[1] = vf[ix][1]; av[2] = vf[ix + 1][0]; av[3] = vf[ix + 1][1];
;           O[db] = mfma32(as_bf16x8(av), pf, O[db]);
;         }
;       }
;       __builtin_amdgcn_s_setprio(0);
;       __builtin_amdgcn_sched_barrier(0);
;     }
.LBB0_528:
	v_mov_b32_e32 v145, v144
	v_pk_fma_f32 v[50:51], v[50:51], s[28:29], v[144:145] op_sel_hi:[1,0,1] neg_lo:[0,0,1] neg_hi:[0,0,1]
	s_nop 0
	v_exp_f32_e32 v98, v50
	v_exp_f32_e32 v99, v51
	v_pk_fma_f32 v[50:51], v[52:53], s[28:29], v[144:145] op_sel_hi:[1,0,1] neg_lo:[0,0,1] neg_hi:[0,0,1]
	s_nop 0
	v_exp_f32_e32 v100, v50
	v_exp_f32_e32 v101, v51
	v_pk_fma_f32 v[50:51], v[54:55], s[28:29], v[144:145] op_sel_hi:[1,0,1] neg_lo:[0,0,1] neg_hi:[0,0,1]
	s_nop 0
	v_exp_f32_e32 v102, v50
	v_exp_f32_e32 v103, v51
	v_pk_fma_f32 v[50:51], v[56:57], s[28:29], v[144:145] op_sel_hi:[1,0,1] neg_lo:[0,0,1] neg_hi:[0,0,1]
	v_cvt_pk_bf16_f32 v52, v102, v103
	v_exp_f32_e32 v104, v50
	v_exp_f32_e32 v105, v51
	v_pk_fma_f32 v[50:51], v[58:59], s[28:29], v[144:145] op_sel_hi:[1,0,1] neg_lo:[0,0,1] neg_hi:[0,0,1]
	v_cvt_pk_bf16_f32 v53, v104, v105
	v_exp_f32_e32 v58, v50
	v_exp_f32_e32 v59, v51
	v_pk_fma_f32 v[50:51], v[60:61], s[28:29], v[144:145] op_sel_hi:[1,0,1] neg_lo:[0,0,1] neg_hi:[0,0,1]
	v_cvt_pk_bf16_f32 v54, v58, v59
	v_exp_f32_e32 v60, v50
	v_exp_f32_e32 v61, v51
	v_pk_fma_f32 v[50:51], v[62:63], s[28:29], v[144:145] op_sel_hi:[1,0,1] neg_lo:[0,0,1] neg_hi:[0,0,1]
	v_cvt_pk_bf16_f32 v55, v60, v61
	v_exp_f32_e32 v62, v50
	v_exp_f32_e32 v63, v51
	v_pk_fma_f32 v[50:51], v[64:65], s[28:29], v[144:145] op_sel_hi:[1,0,1] neg_lo:[0,0,1] neg_hi:[0,0,1]
	v_cvt_pk_bf16_f32 v56, v62, v63
	v_exp_f32_e32 v64, v50
	v_exp_f32_e32 v65, v51
	v_cvt_pk_bf16_f32 v50, v98, v99
	v_cvt_pk_bf16_f32 v51, v100, v101
	v_cvt_pk_bf16_f32 v57, v64, v65
	s_nop 0
	v_mfma_f32_32x32x16_bf16 v[18:33], v[94:97], v[50:53], v[18:33]
	v_mfma_f32_32x32x16_bf16 v[2:17], v[90:93], v[50:53], v[2:17]
	v_add_f32_e64 v50, v98, 0
	v_add_f32_e64 v51, v99, 0
	v_add_f32_e64 v50, v100, v50
	v_add_f32_e64 v51, v101, v51
	v_add_f32_e64 v50, v102, v50
	v_add_f32_e64 v51, v103, v51
	v_add_f32_e32 v50, v104, v50
	v_add_f32_e32 v51, v105, v51
	v_mfma_f32_32x32x16_bf16 v[18:33], v[86:89], v[54:57], v[18:33]
	v_add_f32_e64 v50, v58, v50
	v_add_f32_e64 v51, v59, v51
	v_add_f32_e64 v50, v60, v50
	v_add_f32_e64 v51, v61, v51
	v_add_f32_e64 v50, v62, v50
	v_add_f32_e64 v51, v63, v51
	v_add_f32_e32 v50, v64, v50
	v_add_f32_e32 v51, v65, v51
	v_mfma_f32_32x32x16_bf16 v[2:17], v[82:85], v[54:57], v[2:17]
	s_nop 0
	v_fma_f32 v34, v34, s28, -v144
	v_fma_f32 v35, v35, s28, -v145
	v_exp_f32_e32 v52, v34
	v_exp_f32_e32 v53, v35
	v_pk_fma_f32 v[34:35], v[36:37], s[28:29], v[144:145] op_sel_hi:[1,0,1] neg_lo:[0,0,1] neg_hi:[0,0,1]
	s_nop 0
	v_exp_f32_e32 v54, v34
	v_exp_f32_e32 v55, v35
	v_pk_fma_f32 v[34:35], v[38:39], s[28:29], v[144:145] op_sel_hi:[1,0,1] neg_lo:[0,0,1] neg_hi:[0,0,1]
	s_nop 0
	v_exp_f32_e32 v56, v34
	v_exp_f32_e32 v57, v35
	v_pk_fma_f32 v[34:35], v[40:41], s[28:29], v[144:145] op_sel_hi:[1,0,1] neg_lo:[0,0,1] neg_hi:[0,0,1]
	v_cvt_pk_bf16_f32 v36, v56, v57
	v_exp_f32_e32 v58, v34
	v_exp_f32_e32 v59, v35
	v_pk_fma_f32 v[34:35], v[42:43], s[28:29], v[144:145] op_sel_hi:[1,0,1] neg_lo:[0,0,1] neg_hi:[0,0,1]
	v_cvt_pk_bf16_f32 v37, v58, v59
	v_exp_f32_e32 v42, v34
	v_exp_f32_e32 v43, v35
	v_pk_fma_f32 v[34:35], v[44:45], s[28:29], v[144:145] op_sel_hi:[1,0,1] neg_lo:[0,0,1] neg_hi:[0,0,1]
	v_cvt_pk_bf16_f32 v38, v42, v43
	v_exp_f32_e32 v44, v34
	v_exp_f32_e32 v45, v35
	v_pk_fma_f32 v[34:35], v[46:47], s[28:29], v[144:145] op_sel_hi:[1,0,1] neg_lo:[0,0,1] neg_hi:[0,0,1]
	v_cvt_pk_bf16_f32 v39, v44, v45
	v_exp_f32_e32 v46, v34
	v_exp_f32_e32 v47, v35
	v_pk_fma_f32 v[34:35], v[48:49], s[28:29], v[144:145] op_sel_hi:[1,0,1] neg_lo:[0,0,1] neg_hi:[0,0,1]
; template <int NB>
; DI void softmax_pv(f32x16 (&s)[2], float& mrun, float& lsum, f32x16 (&O)[2], unsigned vaddr) {
;     ...
;   if (NB == 2) {
; #pragma unroll
;     for (int kb = 0; kb < 2; ++kb) {
; #pragma unroll
;       for (int e = 0; e < 16; e += 2) {
;         f32x2 t = {s[kb][e], s[kb][e + 1]};
;         t = t * l2e2 - mb2;
;         f32x2 pv;
;         pv[0] = __builtin_amdgcn_exp2f(t[0]);
;         pv[1] = __builtin_amdgcn_exp2f(t[1]);
;         s[kb][e] = pv[0];
;         s[kb][e + 1] = pv[1];
;         ps2 += pv;
;       }
;       u32x4 pp[2];
; #pragma unroll
;       for (int st = 0; st < 2; ++st)
; #pragma unroll
;         for (int j = 0; j < 4; ++j) pp[st][j] = pk_bf16(s[kb][8 * st + 2 * j], s[kb][8 * st + 2 * j + 1]);
;       __builtin_amdgcn_sched_barrier(0);
;       __builtin_amdgcn_s_setprio(1);
; #pragma unroll
;       for (int st = 0; st < 2; ++st) {
;         const bf16x8 pf = as_bf16x8(pp[st]);
; #pragma unroll
;         for (int db = 0; db < 2; ++db) {
;           const int ix = ((kb * 2 + st) * 2 + db) * 2;
;           u32x4 av;
;           av[0] = vf[ix][0]; av[1] = vf[ix][1]; av[2] = vf[ix + 1][0]; av[3] = vf[ix + 1][1];
;           O[db] = mfma32(as_bf16x8(av), pf, O[db]);
;         }
;       }
;       __builtin_amdgcn_s_setprio(0);
;       __builtin_amdgcn_sched_barrier(0);
;     }
; template <int kind>
; __device__ void attn_job(const Params& p, int layer, int idx, char* smem) {
;     ...
;   lsum = xsum32(lsum);
;   const float inv = 1.f / lsum;
;   u16* dst = p.xn + (size_t)qtok * DM + ocol;
; #pragma unroll
;   for (int db = 0; db < 2; ++db)
; #pragma unroll
;     for (int k = 0; k < 2; ++k) {
;       const int gA = 2 * k, gB = 2 * k + 1;
;       const unsigned x0 = pk_bf16(O[db][4 * gA + 0] * inv, O[db][4 * gA + 1] * inv), x1 = pk_bf16(O[db][4 * gA + 2] * inv, O[db][4 * gA + 3] * inv);
;       const unsigned y0 = pk_bf16(O[db][4 * gB + 0] * inv, O[db][4 * gB + 1] * inv), y1 = pk_bf16(O[db][4 * gB + 2] * inv, O[db][4 * gB + 3] * inv);
;       auto r0 = __builtin_amdgcn_permlane32_swap(x0, y0, false, false);
;       auto r1 = __builtin_amdgcn_permlane32_swap(x1, y1, false, false);
;       u32x4 wv;
;       wv[0] = r0[0]; wv[1] = r1[0]; wv[2] = r0[1]; wv[3] = r1[1];
;       *(u32x4*)(dst + db * 32 + 16 * k + 8 * hh) = wv;
;     }
;   __syncthreads();
	v_cvt_pk_bf16_f32 v40, v46, v47
	v_exp_f32_e32 v48, v34
	v_exp_f32_e32 v49, v35
	v_cvt_pk_bf16_f32 v34, v52, v53
	v_cvt_pk_bf16_f32 v35, v54, v55
	v_cvt_pk_bf16_f32 v41, v48, v49
	s_nop 0
	v_mfma_f32_32x32x16_bf16 v[18:33], v[78:81], v[34:37], v[18:33]
	v_mfma_f32_32x32x16_bf16 v[2:17], v[74:77], v[34:37], v[2:17]
	v_add_f32_e64 v34, v52, v50
	v_add_f32_e64 v35, v53, v51
	v_add_f32_e64 v34, v54, v34
	v_add_f32_e64 v35, v55, v35
	v_add_f32_e64 v34, v56, v34
	v_add_f32_e64 v35, v57, v35
	v_add_f32_e32 v34, v58, v34
	v_add_f32_e32 v35, v59, v35
	v_mfma_f32_32x32x16_bf16 v[18:33], v[70:73], v[38:41], v[18:33]
	v_add_f32_e64 v34, v42, v34
	v_add_f32_e64 v35, v43, v35
	v_add_f32_e64 v34, v44, v34
	v_add_f32_e64 v35, v45, v35
	v_add_f32_e64 v34, v46, v34
	v_add_f32_e64 v35, v47, v35
	v_add_f32_e32 v34, v48, v34
	v_add_f32_e32 v35, v49, v35
	v_mfma_f32_32x32x16_bf16 v[2:17], v[66:69], v[38:41], v[2:17]
	s_nop 0
	v_add_f32_e32 v34, v34, v35
	v_fmac_f32_e32 v34, v106, v0
	v_mov_b32_e32 v0, v34
	s_nop 1
	v_permlane32_swap_b32_e32 v34, v0
	v_add_f32_e32 v0, v34, v0
	v_div_scale_f32 v34, s[2:3], v0, v0, 1.0
	v_rcp_f32_e32 v35, v34
	s_nop 0
	v_fma_f32 v36, -v34, v35, 1.0
	v_fmac_f32_e32 v35, v36, v35
	v_div_scale_f32 v36, vcc, 1.0, v0, 1.0
	v_mul_f32_e32 v37, v36, v35
	v_fma_f32 v38, -v34, v37, v36
	v_fmac_f32_e32 v37, v38, v35
	v_fma_f32 v34, -v34, v37, v36
	v_div_fmas_f32 v34, v34, v35, v37
	v_div_fixup_f32 v34, v34, v0, 1.0
	v_lshlrev_b32_e32 v0, 11, v139
	v_pk_mul_f32 v[18:19], v[18:19], v[34:35] op_sel_hi:[1,0]
	v_pk_mul_f32 v[20:21], v[20:21], v[34:35] op_sel_hi:[1,0]
	v_pk_mul_f32 v[2:3], v[2:3], v[34:35] op_sel_hi:[1,0]
	v_pk_mul_f32 v[4:5], v[4:5], v[34:35] op_sel_hi:[1,0]
	v_lshl_add_u64 v[36:37], s[54:55], 0, v[0:1]
	v_cvt_pk_bf16_f32 v18, v18, v19
	v_cvt_pk_bf16_f32 v19, v20, v21
	v_pk_mul_f32 v[20:21], v[22:23], v[34:35] op_sel_hi:[1,0]
	v_pk_mul_f32 v[22:23], v[24:25], v[34:35] op_sel_hi:[1,0]
	v_cvt_pk_bf16_f32 v2, v2, v3
	v_cvt_pk_bf16_f32 v3, v4, v5
	v_pk_mul_f32 v[4:5], v[6:7], v[34:35] op_sel_hi:[1,0]
	v_pk_mul_f32 v[6:7], v[8:9], v[34:35] op_sel_hi:[1,0]
	v_lshl_add_u64 v[36:37], s[0:1], 1, v[36:37]
	v_lshlrev_b32_e32 v0, 1, v138
	v_cvt_pk_bf16_f32 v20, v20, v21
	v_cvt_pk_bf16_f32 v21, v22, v23
	v_cvt_pk_bf16_f32 v4, v4, v5
	v_cvt_pk_bf16_f32 v5, v6, v7
	v_lshl_add_u64 v[36:37], v[36:37], 0, v[0:1]
	v_permlane32_swap_b32_e32 v18, v20
	v_permlane32_swap_b32_e32 v19, v21
	v_permlane32_swap_b32_e32 v2, v4
	v_permlane32_swap_b32_e32 v3, v5
	global_store_dwordx4 v[36:37], v[18:21], off offset:1024
	global_store_dwordx4 v[36:37], v[2:5], off offset:1088
	v_pk_mul_f32 v[22:23], v[32:33], v[34:35] op_sel_hi:[1,0]
	v_pk_mul_f32 v[18:19], v[26:27], v[34:35] op_sel_hi:[1,0]
	v_pk_mul_f32 v[20:21], v[28:29], v[34:35] op_sel_hi:[1,0]
	v_pk_mul_f32 v[2:3], v[10:11], v[34:35] op_sel_hi:[1,0]
	v_pk_mul_f32 v[4:5], v[12:13], v[34:35] op_sel_hi:[1,0]
	v_cvt_pk_bf16_f32 v18, v18, v19
	v_cvt_pk_bf16_f32 v19, v20, v21
	v_pk_mul_f32 v[20:21], v[30:31], v[34:35] op_sel_hi:[1,0]
	v_cvt_pk_bf16_f32 v2, v2, v3
	v_cvt_pk_bf16_f32 v3, v4, v5
	v_pk_mul_f32 v[4:5], v[14:15], v[34:35] op_sel_hi:[1,0]
	v_pk_mul_f32 v[6:7], v[16:17], v[34:35] op_sel_hi:[1,0]
	v_cvt_pk_bf16_f32 v20, v20, v21
	v_cvt_pk_bf16_f32 v21, v22, v23
	v_cvt_pk_bf16_f32 v4, v4, v5
	v_cvt_pk_bf16_f32 v5, v6, v7
	v_permlane32_swap_b32_e32 v18, v20
	v_permlane32_swap_b32_e32 v19, v21
	v_permlane32_swap_b32_e32 v2, v4
	v_permlane32_swap_b32_e32 v3, v5
	global_store_dwordx4 v[36:37], v[18:21], off offset:1056
	global_store_dwordx4 v[36:37], v[2:5], off offset:1120
	s_barrier
